# attention phase: one static s_setprio 1 for waves 4-7 (younger half) across the item loop, reset to 0 at phase exit
# baseline (speedup 1.0000x reference)
; #define LAS __attribute__((address_space(3)))
; __device__ __forceinline__ void phase_attn_items(const Params& P, LAS unsigned char* lds) {
;     unsigned char* ws = P.ws; asm volatile("" : "+s"(ws));
;     int tid_ = threadIdx.x; asm volatile("" : "+v"(tid_));
;     const int tid = tid_, wave = __builtin_amdgcn_readfirstlane(tid >> 6);
;     const bf16_t* Q = (const bf16_t*)(ws + WS_Q); const bf16_t* Kb = (const bf16_t*)(ws + WS_K); const bf16_t* Vb = (const bf16_t*)(ws + WS_V);
;     bf16_t* OpB = (bf16_t*)(ws + WS_OP); float* LseB = (float*)(ws + WS_LSE);
;     const bool xmap = gridDim.x == 256;
;     for (int it = 0; it < (xmap ? 6 : (3 * 512 + (int)gridDim.x - 1) / (int)gridDim.x); ++it) {
;         int lane = tid & 63; asm volatile("" : "+v"(lane));
;         int pat, b, hh, rc;
;         if (xmap) { const int g = it * 32 + (blockIdx.x >> 3), pair = 4 * (blockIdx.x & 7) + g / 48, within = g % 48; pat = within >> 4; rc = within & 15; b = pair >> 3; hh = pair & 7; }
;         else { const int item = it * gridDim.x + blockIdx.x; if (item >= 3 * 512) break; pat = item >> 9; const int rem = item & 511; b = rem >> 7; hh = (rem >> 4) & 7; rc = rem & 15; }
;         const int dlog = 2 * pat, r = pat == 0 ? 0 : (pat == 1 ? rc >> 2 : rc), ch8 = pat == 0 ? rc : (pat == 1 ? rc & 3 : 0);
;         const int ntile = (SEQ >> dlog) >> 5, ql = lane & 31, h = lane >> 5;
;         const size_t rowbase = (size_t)b * SEQ;
;         const size_t hb = (size_t)hh * 256;
;     ...
;         const int trow = (tid >> 4) & 31, tch = tid & 15;
;         const unsigned roff = (unsigned)((trow << dlog) * AW + tch * 8) * 2u;
;         const unsigned loff = off_b(trow, tch);
.LBB0_111:
	s_andn2_b64 vcc, exec, s[12:13]
	s_cbranch_vccnz .LBB0_263
	s_load_dwordx4 s[4:7], s[0:1], 0x90
	v_mov_b32_e32 v0, v178
	v_writelane_b32 v247, s98, 1
	s_waitcnt lgkmcnt(0)
	s_mov_b64 s[2:3], s[6:7]
	v_writelane_b32 v247, s99, 2
	v_readfirstlane_b32 s4, v0
	s_ashr_i32 s4, s4, 6
	s_cmp_lt_u32 s4, 4
	s_cbranch_scc1 .Lattn_prio_skip
	s_setprio 1
.Lattn_prio_skip:
	s_add_u32 s8, s2, 0xd6e4000
	s_addc_u32 s9, s3, 0
	v_writelane_b32 v247, s8, 3
	s_add_u32 s5, s2, 0xf6e4000
	v_lshrrev_b32_e32 v4, 2, v0
	v_writelane_b32 v247, s9, 4
	v_writelane_b32 v247, s5, 5
	s_addc_u32 s5, s3, 0
	v_writelane_b32 v247, s5, 6
	s_add_u32 s5, s2, 0x116e4000
	v_writelane_b32 v247, s5, 7
	s_addc_u32 s5, s3, 0
	v_writelane_b32 v247, s5, 8
	s_add_u32 s5, s2, 0x196e4000
	v_writelane_b32 v247, s5, 9
	s_addc_u32 s5, s3, 0
	v_writelane_b32 v247, s5, 10
	s_add_u32 s2, s2, 0x1f6e4000
	v_writelane_b32 v247, s2, 11
	s_addc_u32 s2, s3, 0
	v_and_b32_e32 v166, 63, v0
	v_bfe_u32 v167, v0, 4, 5
	v_and_b32_e32 v2, 15, v0
	v_and_b32_e32 v4, 12, v4
	v_bfe_u32 v0, v0, 6, 2
	v_writelane_b32 v247, s2, 12
	v_bitop3_b32 v0, v4, v2, v0 bitop3:0x36
	v_lshlrev_b32_e32 v3, 8, v167
	v_lshlrev_b32_e32 v0, 4, v0
	v_writelane_b32 v247, s4, 13
	s_lshl_b32 s2, s4, 13
	v_add3_u32 v169, 0, v0, v3
	v_writelane_b32 v247, s2, 14
	s_add_i32 s2, s2, 0
	v_lshlrev_b32_e32 v168, 4, v2
	v_writelane_b32 v247, s2, 15
	v_add_u32_e32 v170, 0x10000, v169
	v_add_u32_e32 v171, 0x12000, v169
	v_add_u32_e32 v172, 0x14000, v169
	v_add_u32_e32 v173, 0x16000, v169
	s_mov_b32 s6, -1
	s_mov_b32 s7, s77
	v_readlane_b32 s8, v253, 63
	v_writelane_b32 v247, s77, 16
	s_branch .LBB0_116

; __device__ __forceinline__ void xcd_barrier(const XcdBarrier& b) {
;     asm volatile("s_waitcnt vmcnt(0)" ::: "memory");
;     __syncthreads();
;     if (threadIdx.x == 0) {
;         unsigned* bar = b.bar;
;         __builtin_amdgcn_s_waitcnt(0);
;         unsigned nloc = b.st[0], nx = b.st[1];
;         if (nloc == 0u) { xcd_barrier_complete(bar, b.x, nloc, nx); b.st[0] = nloc; b.st[1] = nx; }
.LBB0_197:
	s_setprio 0
	s_waitcnt vmcnt(0)
	s_barrier
	s_and_saveexec_b64 s[2:3], s[92:93]
	v_readlane_b32 s98, v247, 1
	s_xor_b64 s[12:13], exec, s[2:3]
	v_readlane_b32 s77, v247, 16
	v_readlane_b32 s99, v247, 2
	s_cbranch_execz .LBB0_250
	v_readlane_b32 s2, v252, 29
	s_waitcnt vmcnt(0) expcnt(0) lgkmcnt(0)
	s_nop 0
	v_mov_b32_e32 v0, s2
	ds_read_b32 v3, v0
	v_readlane_b32 s2, v252, 30
	s_waitcnt lgkmcnt(0)
	v_cmp_ne_u32_e32 vcc, 0, v3
	v_mov_b32_e32 v0, s2
	ds_read_b32 v2, v0
	s_cbranch_vccnz .LBB0_213
	s_mov_b32 s2, 1
	s_branch .LBB0_201
